# X53: X52 with the XCD-local seam flag additionally requiring the grid size to be a multiple of 8 (the tile-to-XCD ownership the local seams rely on only holds then)
# speedup vs baseline: 1.0034x; 1.0000x over previous
; #define GAS __attribute__((address_space(1)))
; __device__ __forceinline__ unsigned xb_ld(unsigned* p)              { return __hip_atomic_load(p, __ATOMIC_RELAXED, __HIP_MEMORY_SCOPE_AGENT); }
; __device__ __forceinline__ void xcd_barrier_complete(unsigned* bar, unsigned x, unsigned& nloc, unsigned& nx) {
;     const unsigned G = gridDim.x * gridDim.y * gridDim.z;
;     unsigned sum, cnt, mine, sp = 0u;
;     for (;;) {
;         sum = 0u; cnt = 0u; mine = 0u;
; #pragma unroll
;         for (unsigned j = 0; j < 16; ++j) { const unsigned c = xb_ld(&bar[XB_XCNT(j)]); sum += c; cnt += (c > 0u) ? 1u : 0u; mine = (j == x) ? c : mine; }
;         if (sum == G) break;
;         __builtin_amdgcn_s_sleep(1);
;         if ((++sp & 255u) == 0u) { if (xb_ld(&bar[XB_TMO])) break; if (sp > XB_SPIN_CAP) { atomicAdd(&bar[XB_TMO], 1u); break; } }
;     }
;     nloc = mine > 0u ? mine : 1u; nx = cnt > 0u ? cnt : 1u;
; }
; __global__ void __launch_bounds__(NTHR, 2) fwd_kernel(Args args) {
;     ...
;     for (int f = 0; f < 2 * DEPTH; ++f) {
;         const int l = f >> 1, second = f & 1, base = 1 + 8 * f;
;         unsigned long long wsv_ = (unsigned long long)args.ws, outv_ = (unsigned long long)args.out; asm volatile("" : "+s"(wsv_), "+s"(outv_));
;         unsigned char* ws = (unsigned char*)(GAS unsigned char*)wsv_; float* out = (float*)(GAS float*)outv_; rs_t* rowss_all = (rs_t*)(ws + WS_ROWSS);
;         int tid = tid0; asm volatile("" : "+v"(tid));
;         const int lane = tid & 63, wave = __builtin_amdgcn_readfirstlane(tid >> 6), gw = vcu * NWAVES + wave;
;         bf16* XB = (bf16*)(ws + WS_XB); bf16* HP = (bf16*)(ws + WS_HP); bf16* Y = (bf16*)(ws + WS_Y);
;         const rs_t* rs_in = rowss_all + (size_t)(3 * l + 2 * second) * M;
;         rs_t* rs_out = rowss_all + (size_t)(3 * l + 1 + 2 * second) * M;
;         if (IN(base + 1)) {
;             pg8::Gemm g{XB, (const bf16*)(ws + (second ? WS_WGU2 : WS_WGU1)), M, NGU, DM}; pg8::StaticOrder S; S.init(M, NGU, G, bx);
.LBB0_198:
	v_readlane_b32 s5, v252, 4
	s_cmpk_lt_i32 s5, 0x1600
	s_cselect_b64 s[0:1], -1, 0
	v_writelane_b32 v252, s0, 56
	s_ashr_i32 s4, s5, 31
	s_ashr_i32 s63, s62, 31
	v_writelane_b32 v252, s1, 57
	s_lshr_b32 s0, s4, 29
	s_add_i32 s1, s5, s0
	s_ashr_i32 s0, s1, 3
	s_and_b32 s1, s1, -8
	s_sub_i32 s1, s5, s1
	s_add_u32 s6, s78, 0x1200
	s_addc_u32 s7, s79, 0
	v_writelane_b32 v252, s6, 58
	s_waitcnt lgkmcnt(0)
	v_mov_b32_e32 v5, 0
	v_mov_b32_e32 v194, 0x358637bd
	v_writelane_b32 v252, s7, 59
	s_add_u32 s6, s78, 0x1400
	s_addc_u32 s7, s79, 0
	v_writelane_b32 v252, s6, 60
	v_mov_b32_e32 v195, 1
	v_mov_b32_e32 v196, 0x3ecc95a3
	v_writelane_b32 v252, s7, 61
	s_add_u32 s6, s78, 0x1500
	s_addc_u32 s7, s79, 0
	v_writelane_b32 v252, s6, 62
	v_mov_b32_e32 v197, 0x3d2aaaab
	v_mov_b32_e32 v198, 0x260
	v_writelane_b32 v252, s7, 63
	s_add_u32 s6, s78, 0x1600
	s_addc_u32 s7, s79, 0
	v_writelane_b32 v253, s6, 0
	v_mov_b32_e32 v159, 0x41000000
	v_mov_b64_e32 v[160:161], 0xbff
	v_writelane_b32 v253, s7, 1
	s_add_u32 s6, s78, 0x1700
	s_addc_u32 s7, s79, 0
	v_writelane_b32 v253, s6, 2
	v_mov_b32_e32 v162, 0x3f317218
	v_mov_b32_e32 v200, 0x7f800000
	v_writelane_b32 v253, s7, 3
	s_add_u32 s6, s78, 0x1800
	s_addc_u32 s7, s79, 0
	v_writelane_b32 v253, s6, 4
	v_mov_b32_e32 v201, 0x7fc00000
	v_mov_b32_e32 v202, 0xff800000
	v_writelane_b32 v253, s7, 5
	s_add_u32 s6, s78, 0x1900
	s_addc_u32 s7, s79, 0
	v_writelane_b32 v253, s6, 6
	v_mov_b32_e32 v203, 0x3000
	v_mov_b32_e32 v204, 0x1800
	v_writelane_b32 v253, s7, 7
	s_add_u32 s6, s78, 0x1a00
	s_addc_u32 s7, s79, 0
	v_writelane_b32 v253, s6, 8
	v_mov_b32_e32 v205, 0x3fff
	v_mov_b32_e32 v206, 0xf149f2ca
	v_writelane_b32 v253, s7, 9
	s_add_u32 s6, s78, 0x1b00
	s_addc_u32 s7, s79, 0
	v_writelane_b32 v253, s6, 10
	v_mov_b32_e32 v207, 0x60
	v_mov_b32_e32 v208, 0xe400
	v_writelane_b32 v253, s7, 11
	s_add_u32 s6, s78, 0x1c00
	s_addc_u32 s7, s79, 0
	v_writelane_b32 v253, s6, 12
	v_mov_b32_e32 v209, 0xa000
	v_mov_b64_e32 v[164:165], 0x400
	v_writelane_b32 v253, s7, 13
	s_add_u32 s6, s78, 0x1d00
	s_addc_u32 s7, s79, 0
	v_writelane_b32 v253, s6, 14
	v_mov_b64_e32 v[166:167], 0x3ff
	s_movk_i32 s75, 0x800
	v_writelane_b32 v253, s7, 15
	s_add_u32 s6, s78, 0x1e00
	s_addc_u32 s7, s79, 0
	v_writelane_b32 v253, s6, 16
	s_movk_i32 s77, 0x6000
	s_mov_b32 s71, 0x44800000
	v_writelane_b32 v253, s7, 17
	s_add_u32 s6, s78, 0x1f00
	s_addc_u32 s7, s79, 0
	v_writelane_b32 v253, s6, 18
	s_movk_i32 s73, 0x3000
	s_mov_b32 s69, 0x60000
	v_writelane_b32 v253, s7, 19
	s_add_u32 s6, s78, 0x2000
	s_addc_u32 s7, s79, 0
	v_writelane_b32 v253, s6, 20
	s_mov_b32 s68, 0xbe800000
	s_movk_i32 s70, 0x110
	v_writelane_b32 v253, s7, 21
	s_add_u32 s6, s78, 0x2100
	s_addc_u32 s7, s79, 0
	v_writelane_b32 v253, s6, 22
	s_mov_b64 s[30:31], 0x1000
	s_nop 0
	v_writelane_b32 v253, s7, 23
	s_add_u32 s6, s78, 0x2200
	s_addc_u32 s7, s79, 0
	v_writelane_b32 v253, s6, 24
	s_nop 1
	v_writelane_b32 v253, s7, 25
	s_add_u32 s6, s78, 0x2300
	s_addc_u32 s7, s79, 0
	v_writelane_b32 v253, s6, 26
	s_cmp_eq_u32 s2, 15
	s_nop 0
	v_writelane_b32 v253, s7, 27
	s_cselect_b64 s[6:7], -1, 0
	v_writelane_b32 v253, s6, 28
	s_cmp_eq_u32 s2, 14
	s_nop 0
	v_writelane_b32 v253, s7, 29
	s_cselect_b64 s[6:7], -1, 0
	v_writelane_b32 v253, s6, 30
	s_cmp_eq_u32 s2, 13
	s_nop 0
	v_writelane_b32 v253, s7, 31
	s_cselect_b64 s[6:7], -1, 0
	v_writelane_b32 v253, s6, 32
	s_cmp_eq_u32 s2, 12
	s_nop 0
	v_writelane_b32 v253, s7, 33
	s_cselect_b64 s[6:7], -1, 0
	v_writelane_b32 v253, s6, 34
	s_cmp_eq_u32 s2, 11
	s_nop 0
	v_writelane_b32 v253, s7, 35
	s_cselect_b64 s[6:7], -1, 0
	v_writelane_b32 v253, s6, 36
	s_cmp_eq_u32 s2, 10
	s_nop 0
	v_writelane_b32 v253, s7, 37
	s_cselect_b64 s[6:7], -1, 0
	v_writelane_b32 v253, s6, 38
	s_cmp_eq_u32 s2, 9
	s_nop 0
	v_writelane_b32 v253, s7, 39
	s_cselect_b64 s[6:7], -1, 0
	v_writelane_b32 v253, s6, 40
	s_cmp_eq_u32 s2, 8
	s_nop 0
	v_writelane_b32 v253, s7, 41
	s_cselect_b64 s[6:7], -1, 0
	v_writelane_b32 v253, s6, 42
	s_cmp_eq_u32 s2, 7
	s_nop 0
	v_writelane_b32 v253, s7, 43
	s_cselect_b64 s[6:7], -1, 0
	v_writelane_b32 v253, s6, 44
	s_cmp_eq_u32 s2, 6
	s_nop 0
	v_writelane_b32 v253, s7, 45
	s_cselect_b64 s[6:7], -1, 0
	v_writelane_b32 v253, s6, 46
	s_cmp_eq_u32 s2, 5
	s_nop 0
	v_writelane_b32 v253, s7, 47
	s_cselect_b64 s[6:7], -1, 0
	v_writelane_b32 v253, s6, 48
	s_cmp_eq_u32 s2, 4
	s_nop 0
	v_writelane_b32 v253, s7, 49
	s_cselect_b64 s[6:7], -1, 0
	v_writelane_b32 v253, s6, 50
	s_cmp_eq_u32 s2, 3
	s_nop 0
	v_writelane_b32 v253, s7, 51
	s_cselect_b64 s[6:7], -1, 0
	v_writelane_b32 v253, s6, 52
	s_cmp_eq_u32 s2, 2
	s_nop 0
	v_writelane_b32 v253, s7, 53
	s_cselect_b64 s[6:7], -1, 0
	v_writelane_b32 v253, s6, 54
	s_cmp_eq_u32 s2, 1
	s_nop 0
	v_writelane_b32 v253, s7, 55
	s_cselect_b64 s[6:7], -1, 0
	v_writelane_b32 v253, s6, 56
	s_cmp_eq_u32 s2, 0
	s_nop 0
	v_writelane_b32 v253, s7, 57
	s_cselect_b64 s[6:7], -1, 0
	s_lshl_b32 s2, s2, 8
	s_add_u32 s2, s20, s2
	v_writelane_b32 v253, s6, 58
	s_addc_u32 s3, s21, 0
	s_nop 0
	v_writelane_b32 v253, s7, 59
	s_add_u32 s6, s2, 0x1400
	s_addc_u32 s7, s3, 0
	v_writelane_b32 v253, s6, 60
	s_add_u32 s2, s2, 0x2400
	s_addc_u32 s3, s3, 0
	v_writelane_b32 v253, s7, 61
	v_writelane_b32 v253, s2, 62
	s_nop 1
	v_writelane_b32 v253, s3, 63
	s_add_u32 s2, s78, 0x4400
	s_addc_u32 s3, s79, 0
	v_writelane_b32 v254, s2, 0
	s_nop 1
	v_writelane_b32 v254, s3, 1
	s_add_u32 s2, s78, 0x4500
	s_addc_u32 s3, s79, 0
	v_writelane_b32 v254, s2, 2
	s_cmpk_lt_i32 s5, 0x400
	s_movk_i32 s78, 0x90
	v_writelane_b32 v254, s3, 3
	s_cselect_b64 s[2:3], -1, 0
	v_writelane_b32 v254, s2, 4
	s_mov_b32 s79, 0xf800000
	s_nop 0
	v_writelane_b32 v254, s3, 5
	s_sub_u32 s2, 0x400, s5
; __global__ void __launch_bounds__(NTHR, 2) fwd_kernel(Args args) {
;     ...
;     const int G = gridDim.x, bx = blockIdx.x, vcu = (G % 8 == 0) ? (bx % 8) * (G / 8) + bx / 8 : bx;
;     ...
;             pg8::Gemm g{XB, (const bf16*)(ws + (second ? WS_WGU2 : WS_WGU1)), M, NGU, DM}; pg8::StaticOrder S; S.init(M, NGU, G, bx);
;     ...
;             pg8::Gemm g{HP, (const bf16*)(ws + (second ? WS_WD2 : WS_WD1)), M, DM, DFF}; pg8::StaticOrderT<4, true> S; S.init(M, DM, G, bx);
;     ...
;                 pg8::Gemm g{XB, (const bf16*)(ws + WS_WIN), M, NPROJ, DM}; pg8::StaticOrder S; S.init(M, NPROJ, G, bx);
	v_writelane_b32 v254, s4, 6
	s_subb_u32 s3, 0, s4
	v_writelane_b32 v254, s2, 7
	s_cmpk_lt_i32 s5, 0xc00
	s_nop 0
	v_writelane_b32 v254, s3, 8
	s_cselect_b64 s[2:3], -1, 0
	v_writelane_b32 v254, s2, 9
	s_nop 1
	v_writelane_b32 v254, s3, 10
	s_and_b32 s2, s96, 1
	s_cmp_eq_u32 s2, 0
	s_cselect_b64 s[4:5], -1, 0
	v_writelane_b32 v254, s4, 11
	s_cmp_eq_u32 s2, 1
	s_cselect_b64 s[2:3], -1, 0
	v_writelane_b32 v254, s5, 12
	v_writelane_b32 v254, s2, 13
	s_cmpk_lt_i32 s96, 0x200
	s_nop 0
	v_writelane_b32 v254, s3, 14
	s_cselect_b64 s[2:3], -1, 0
	v_writelane_b32 v254, s2, 15
	s_nop 1
	v_writelane_b32 v254, s3, 16
	s_lshl_b32 s2, s96, 7
	s_and_b32 s2, s2, 0x180
	v_writelane_b32 v254, s2, 17
	s_ashr_i32 s2, s96, 10
	s_ashr_i32 s3, s2, 31
	s_lshl_b64 s[4:5], s[2:3], 14
	s_lshl_b32 s2, s96, 4
	s_and_b32 s3, s2, 0x3fc0
	s_or_b32 s6, s4, s3
	s_cmpk_lt_i32 s96, 0x800
	s_cselect_b64 s[8:9], -1, 0
	v_writelane_b32 v254, s8, 18
	s_and_b32 s3, s2, 0x3ff0
	s_add_i32 s7, s3, 0xffffff80
	v_writelane_b32 v254, s9, 19
	v_writelane_b32 v254, s7, 20
	s_or_b32 s7, s4, 16
	v_writelane_b32 v254, s7, 21
	s_or_b32 s7, s4, 24
	v_writelane_b32 v254, s7, 22
	v_writelane_b32 v254, s3, 23
	s_addk_i32 s3, 0xffa0
	s_cmpk_lt_i32 s96, 0x104
	v_writelane_b32 v254, s3, 24
	s_cselect_b64 s[8:9], -1, 0
	s_and_b32 s3, s2, 0x3f00
	s_and_b32 s20, s96, 15
	v_writelane_b32 v254, s8, 25
	s_or_b32 s3, s3, s20
	s_cmpk_lt_i32 s96, 0x400
	v_writelane_b32 v254, s9, 26
	v_writelane_b32 v254, s3, 27
	s_cselect_b64 s[8:9], -1, 0
	v_writelane_b32 v254, s8, 28
	s_cmpk_gt_i32 s96, 0x3ff
	s_mul_i32 s20, s1, 0x81
	v_writelane_b32 v254, s9, 29
	s_cselect_b64 s[8:9], -1, 0
	s_lshl_b32 s3, s1, 7
	s_cmp_lt_i32 s1, 0
	s_movk_i32 s7, 0x2c1
	s_cselect_b32 s3, s20, s3
	s_cselect_b32 s20, s7, 0x2c0
	s_mul_i32 s20, s1, s20
	s_movk_i32 s7, 0x181
	s_cselect_b32 s21, s7, 0x180
	s_add_i32 s20, s20, s0
	s_mul_hi_i32 s22, s20, 0x2e8ba2e9
	s_lshr_b32 s23, s22, 31
	s_ashr_i32 s22, s22, 6
	s_add_i32 s22, s22, s23
	s_mul_i32 s23, s22, 0x160
	s_sub_i32 s20, s20, s23
	s_bfe_u32 s23, s20, 0x3001c
	s_mul_i32 s1, s1, s21
	s_add_i32 s23, s20, s23
	s_add_i32 s1, s1, s0
	s_and_b32 s24, s23, 0xfff8
	s_mul_hi_i32 s21, s1, 0x2aaaaaab
	s_sub_i32 s20, s20, s24
	s_lshr_b32 s24, s21, 31
	s_ashr_i32 s21, s21, 5
	s_add_i32 s21, s21, s24
	s_mul_i32 s24, s21, 0xc0
	s_abs_i32 s28, s62
	s_sub_i32 s1, s1, s24
	v_cvt_f32_u32_e32 v1, s28
	s_bfe_u32 s24, s1, 0x3001c
	s_add_i32 s24, s1, s24
	s_and_b32 s25, s24, 0xfff8
	s_add_i32 s0, s3, s0
	s_sub_i32 s25, s1, s25
	s_ashr_i32 s1, s0, 31
	v_rcp_iflag_f32_e32 v1, v1
	s_lshr_b32 s1, s1, 27
	s_add_i32 s3, s0, s1
	s_and_b32 s1, s3, 0xffe0
	s_sub_i32 s0, s0, s1
	v_mul_f32_e32 v1, 0x4f7ffffe, v1
	s_bfe_i32 s1, s0, 0x80000
	v_cvt_u32_f32_e32 v1, v1
	s_bfe_u32 s1, s1, 0x2000d
	s_add_i32 s26, s0, s1
	s_and_b32 s1, s26, 0xfc
	s_sub_i32 s27, s0, s1
	s_sub_i32 s0, 0, s28
	v_readfirstlane_b32 s1, v1
	s_mul_i32 s0, s0, s1
	s_mul_hi_u32 s0, s1, s0
	v_writelane_b32 v254, s8, 30
	s_add_i32 s29, s1, s0
	s_lshl_b32 s0, s22, 3
	s_sext_i32_i16 s1, s23
	s_sext_i32_i16 s20, s20
	v_writelane_b32 v254, s9, 31
	s_add_i32 s10, s0, s20
	s_ashr_i32 s0, s1, 3
	v_writelane_b32 v254, s0, 32
	s_lshr_b32 s0, s1, 3
	s_bfe_i64 s[0:1], s[0:1], 0x100000
	s_lshl_b64 s[0:1], s[0:1], 20
	v_writelane_b32 v254, s0, 33
	s_sext_i32_i16 s20, s25
	s_mov_b32 s8, s10
	v_writelane_b32 v254, s1, 34
	s_lshl_b32 s0, s21, 3
	s_sext_i32_i16 s1, s24
	s_add_i32 s12, s0, s20
	s_ashr_i32 s0, s1, 3
	v_writelane_b32 v254, s0, 35
	s_lshr_b32 s0, s1, 3
	s_bfe_i64 s[0:1], s[0:1], 0x100000
	s_lshl_b64 s[0:1], s[0:1], 20
	v_writelane_b32 v254, s0, 36
	s_ashr_i32 s11, s10, 31
	s_ashr_i32 s13, s12, 31
	v_writelane_b32 v254, s1, 37
	s_ashr_i32 s0, s3, 5
	s_bfe_i32 s1, s26, 0x80000
	s_lshl_b32 s0, s0, 2
	s_sext_i32_i16 s1, s1
	s_sext_i32_i8 s3, s27
	s_add_i32 s14, s0, s3
	s_ashr_i32 s0, s1, 2
	v_writelane_b32 v254, s0, 38
	s_lshr_b32 s0, s1, 2
	s_bfe_i64 s[0:1], s[0:1], 0x100000
	s_lshl_b64 s[0:1], s[0:1], 20
	v_writelane_b32 v254, s0, 39
	s_ashr_i32 s15, s14, 31
	s_movk_i32 s21, 0x80
	v_writelane_b32 v254, s1, 40
	v_writelane_b32 v254, s8, 41
	s_lshr_b32 s0, s29, 22
	s_mul_i32 s1, s0, s28
	v_writelane_b32 v254, s9, 42
	s_lshl_b64 s[8:9], s[10:11], 20
	v_writelane_b32 v254, s8, 43
	s_sub_i32 s1, 0x400, s1
	s_sub_i32 s3, s1, s28
	v_writelane_b32 v254, s9, 44
	s_mov_b32 s8, s12
	v_writelane_b32 v254, s8, 45
	s_add_i32 s20, s0, 1
	v_mbcnt_lo_u32_b32 v1, -1, 0
	v_writelane_b32 v254, s9, 46
	s_lshl_b64 s[8:9], s[12:13], 20
	v_writelane_b32 v254, s8, 47
	v_mbcnt_hi_u32_b32 v199, -1, v1
	s_mov_b32 s25, 0
	v_writelane_b32 v254, s9, 48
	s_mov_b32 s8, s14
	v_writelane_b32 v254, s8, 49
	s_nop 1
	v_writelane_b32 v254, s9, 50
	s_lshl_b64 s[8:9], s[14:15], 20
	s_cmp_ge_u32 s1, s28
	s_cselect_b32 s1, s3, s1
	s_cselect_b32 s0, s20, s0
	s_sub_i32 s3, s1, s28
	s_add_i32 s20, s0, 1
	s_cmp_ge_u32 s1, s28
	s_cselect_b32 s1, s3, s1
	v_writelane_b32 v254, s8, 51
	s_cselect_b32 s0, s20, s0
	s_cmp_eq_u32 s1, 0
	v_writelane_b32 v254, s9, 52
	s_cselect_b64 s[8:9], -1, 0
	s_xor_b32 s0, s0, s63
	v_writelane_b32 v254, s8, 53
	s_sub_i32 s0, s0, s63
	s_add_i32 s1, s0, -1
	v_writelane_b32 v254, s9, 54
	v_writelane_b32 v254, s1, 55
	v_writelane_b32 v254, s0, 56
	s_mul_i32 s0, s0, s62
	s_cmpk_eq_i32 s0, 0x400
	s_cselect_b64 s[0:1], -1, 0
	v_writelane_b32 v254, s0, 57
	s_ashr_i32 s97, s96, 31
	s_mov_b64 s[28:29], 0x80
	v_writelane_b32 v254, s1, 58
	s_lshl_b64 s[0:1], s[96:97], 17
	s_add_u32 s0, s0, 0x32a00080
	v_writelane_b32 v254, s0, 59
	s_addc_u32 s0, s1, 0
	v_writelane_b32 v254, s0, 60
	v_writelane_b32 v254, s4, 61
	s_mov_b32 s7, s5
	s_add_i32 s0, s96, s62
	v_writelane_b32 v254, s5, 62
	v_writelane_b32 v254, s6, 63
	s_lshl_b32 s0, s0, 4
	s_add_i32 s76, 0, 0x11400
	v_writelane_b32 v255, s7, 0
	v_writelane_b32 v255, s0, 1
	s_sub_i32 s0, s2, 64
	v_writelane_b32 v255, s0, 2
	s_lshl_b32 s0, s62, 4
	v_writelane_b32 v255, s0, 3
	s_add_i32 s0, s96, 0xffffff7c
	v_writelane_b32 v255, s0, 4
	v_readlane_b32 s0, v252, 38
	s_sub_i32 s0, s0, 32
	v_cmp_eq_u32_e64 s[2:3], 0, v0
	v_writelane_b32 v255, s0, 5
	s_mov_b32 s0, s96
	v_writelane_b32 v255, s0, 6
	s_nop 1
	v_writelane_b32 v255, s1, 7
	s_lshl_b32 s0, s96, 8
	v_writelane_b32 v255, s0, 8
	s_lshl_b32 s0, s62, 8
	v_writelane_b32 v255, s0, 9
	s_add_i32 s0, 0, 0x23040
	v_writelane_b32 v255, s0, 10
	s_add_i32 s0, 0, 0x10400
	v_writelane_b32 v255, s0, 11
	s_add_i32 s0, 0, 0x20800
	v_writelane_b32 v255, s0, 12
	v_writelane_b32 v255, s2, 13
	s_mov_b32 s0, 0
	s_nop 0
	v_writelane_b32 v255, s3, 14
	v_readlane_b32 s2, v252, 58
	v_readlane_b32 s3, v252, 59
	v_mov_b32_e32 v247, 0
	s_nop 4
	global_load_dword v247, v247, s[2:3] offset:4 sc1
	s_waitcnt vmcnt(0)
	v_readfirstlane_b32 s2, v247
	s_bcnt1_i32_b32 s2, s2
	s_cmp_eq_u32 s2, 1
	s_cselect_b32 s2, 1, 0
	s_and_b32 s3, s62, 7
	s_cmp_eq_u32 s3, 0
	s_cselect_b32 s2, s2, 0
	v_writelane_b32 v255, s2, 41
	s_lshl_b64 s[2:3], s[62:63], 17
	v_writelane_b32 v255, s2, 15
	s_nop 1
	v_writelane_b32 v255, s3, 16
	s_branch .LBB0_202
